# grid barrier: last XCD leader bumps all per-XCD generation words directly (non-last leaders no longer relay)
# speedup vs baseline: 1.0131x; 1.0027x over previous
.LBB0_66:
	s_or_b64 exec, exec, s[4:5]
	s_and_saveexec_b64 s[4:5], s[8:9]
	s_cbranch_execz .LBB0_68
	v_mov_b32_e32 v2, 1
	global_atomic_add v[0:1], v2, off
	v_mov_b32_e32 v3, 0x2400
	global_atomic_add v3, v2, s[90:91]
	global_atomic_add v3, v2, s[90:91] offset:256
	global_atomic_add v3, v2, s[90:91] offset:512
	global_atomic_add v3, v2, s[90:91] offset:768
	global_atomic_add v3, v2, s[90:91] offset:1024
	global_atomic_add v3, v2, s[90:91] offset:1280
	global_atomic_add v3, v2, s[90:91] offset:1536
	global_atomic_add v3, v2, s[90:91] offset:1792
	global_atomic_add v3, v2, s[90:91] offset:2048
	global_atomic_add v3, v2, s[90:91] offset:2304
	global_atomic_add v3, v2, s[90:91] offset:2560
	global_atomic_add v3, v2, s[90:91] offset:2816
	global_atomic_add v3, v2, s[90:91] offset:3072
	global_atomic_add v3, v2, s[90:91] offset:3328
	global_atomic_add v3, v2, s[90:91] offset:3584
	global_atomic_add v3, v2, s[90:91] offset:3840
.LBB0_68:
	s_or_b64 exec, exec, s[4:5]
.LBB0_69:
	s_or_b64 exec, exec, s[0:1]
	s_waitcnt lgkmcnt(0)
	s_barrier

.LBB0_312:
	s_or_b64 exec, exec, s[6:7]
	s_and_saveexec_b64 s[6:7], s[10:11]
	s_cbranch_execz .LBB0_314
	v_mov_b32_e32 v2, 1
	global_atomic_add v[0:1], v2, off
	v_mov_b32_e32 v3, 0x2400
	global_atomic_add v3, v2, s[90:91]
	global_atomic_add v3, v2, s[90:91] offset:256
	global_atomic_add v3, v2, s[90:91] offset:512
	global_atomic_add v3, v2, s[90:91] offset:768
	global_atomic_add v3, v2, s[90:91] offset:1024
	global_atomic_add v3, v2, s[90:91] offset:1280
	global_atomic_add v3, v2, s[90:91] offset:1536
	global_atomic_add v3, v2, s[90:91] offset:1792
	global_atomic_add v3, v2, s[90:91] offset:2048
	global_atomic_add v3, v2, s[90:91] offset:2304
	global_atomic_add v3, v2, s[90:91] offset:2560
	global_atomic_add v3, v2, s[90:91] offset:2816
	global_atomic_add v3, v2, s[90:91] offset:3072
	global_atomic_add v3, v2, s[90:91] offset:3328
	global_atomic_add v3, v2, s[90:91] offset:3584
	global_atomic_add v3, v2, s[90:91] offset:3840
.LBB0_314:
	s_or_b64 exec, exec, s[6:7]
.LBB0_315:
	s_or_b64 exec, exec, s[2:3]
	s_waitcnt lgkmcnt(0)
	s_barrier

.LBB0_543:
	s_or_b64 exec, exec, s[4:5]
.LBB0_544:
	s_or_b64 exec, exec, s[0:1]
	s_waitcnt lgkmcnt(0)
	s_barrier

.LBB0_644:
	s_or_b64 exec, exec, s[4:5]
.LBB0_645:
	s_or_b64 exec, exec, s[0:1]
	s_waitcnt lgkmcnt(0)
	s_barrier

.LBB0_778:
	s_or_b64 exec, exec, s[6:7]
.LBB0_779:
	s_or_b64 exec, exec, s[0:1]
	s_waitcnt lgkmcnt(0)
	s_barrier

.LBB0_872:
	s_or_b64 exec, exec, s[4:5]
	s_and_saveexec_b64 s[4:5], s[10:11]
	s_cbranch_execz .LBB0_874
	v_mov_b32_e32 v2, 1
	global_atomic_add v[0:1], v2, off
	v_mov_b32_e32 v3, 0x2400
	global_atomic_add v3, v2, s[90:91]
	global_atomic_add v3, v2, s[90:91] offset:256
	global_atomic_add v3, v2, s[90:91] offset:512
	global_atomic_add v3, v2, s[90:91] offset:768
	global_atomic_add v3, v2, s[90:91] offset:1024
	global_atomic_add v3, v2, s[90:91] offset:1280
	global_atomic_add v3, v2, s[90:91] offset:1536
	global_atomic_add v3, v2, s[90:91] offset:1792
	global_atomic_add v3, v2, s[90:91] offset:2048
	global_atomic_add v3, v2, s[90:91] offset:2304
	global_atomic_add v3, v2, s[90:91] offset:2560
	global_atomic_add v3, v2, s[90:91] offset:2816
	global_atomic_add v3, v2, s[90:91] offset:3072
	global_atomic_add v3, v2, s[90:91] offset:3328
	global_atomic_add v3, v2, s[90:91] offset:3584
	global_atomic_add v3, v2, s[90:91] offset:3840
.LBB0_874:
	s_or_b64 exec, exec, s[4:5]
.LBB0_875:
	s_or_b64 exec, exec, s[0:1]
	s_waitcnt lgkmcnt(0)
	s_barrier

.LBB0_980:
	s_or_b64 exec, exec, s[6:7]
.LBB0_981:
	s_or_b64 exec, exec, s[2:3]
	s_waitcnt lgkmcnt(0)
	s_barrier

.LBB0_1069:
	s_or_b64 exec, exec, s[6:7]
.LBB0_1070:
	s_or_b64 exec, exec, s[0:1]
	s_waitcnt lgkmcnt(0)
	s_barrier

.LBB0_1166:
	s_or_b64 exec, exec, s[6:7]
.LBB0_1167:
	s_or_b64 exec, exec, s[2:3]
	s_waitcnt lgkmcnt(0)
	s_barrier

.LBB0_1224:
	s_or_b64 exec, exec, s[6:7]
.LBB0_1225:
	s_or_b64 exec, exec, s[0:1]
	s_waitcnt lgkmcnt(0)
	s_barrier

.LBB0_1299:
	s_or_b64 exec, exec, s[6:7]
.LBB0_1300:
	s_or_b64 exec, exec, s[2:3]
	s_waitcnt lgkmcnt(0)
	s_barrier

.LBB0_1408:
	s_or_b64 exec, exec, s[6:7]
.LBB0_1409:
	s_or_b64 exec, exec, s[0:1]
	s_waitcnt lgkmcnt(0)
	s_barrier

.LBB0_1466:
	s_or_b64 exec, exec, s[6:7]
.LBB0_1467:
	s_or_b64 exec, exec, s[2:3]
	s_waitcnt lgkmcnt(0)
	s_barrier

.LBB0_1695:
	s_or_b64 exec, exec, s[4:5]
.LBB0_1696:
	s_or_b64 exec, exec, s[0:1]
	s_waitcnt lgkmcnt(0)
	s_barrier

.LBB0_1796:
	s_or_b64 exec, exec, s[4:5]
.LBB0_1797:
	s_or_b64 exec, exec, s[0:1]
	s_waitcnt lgkmcnt(0)
	s_barrier

.LBB0_1930:
	s_or_b64 exec, exec, s[6:7]
.LBB0_1931:
	s_or_b64 exec, exec, s[0:1]
	s_waitcnt lgkmcnt(0)
	s_barrier

.LBB0_2026:
	s_or_b64 exec, exec, s[4:5]
.LBB0_2027:
	s_or_b64 exec, exec, s[0:1]
	s_waitcnt lgkmcnt(0)
	s_barrier

.LBB0_2132:
	s_or_b64 exec, exec, s[6:7]
.LBB0_2133:
	s_or_b64 exec, exec, s[2:3]
	s_waitcnt lgkmcnt(0)
	s_barrier

.LBB0_2221:
	s_or_b64 exec, exec, s[6:7]
.LBB0_2222:
	s_or_b64 exec, exec, s[0:1]
	s_waitcnt lgkmcnt(0)
	s_barrier

.LBB0_2318:
	s_or_b64 exec, exec, s[6:7]
.LBB0_2319:
	s_or_b64 exec, exec, s[2:3]
	s_waitcnt lgkmcnt(0)
	s_barrier

.LBB0_2376:
	s_or_b64 exec, exec, s[6:7]
.LBB0_2377:
	s_or_b64 exec, exec, s[0:1]
	s_waitcnt lgkmcnt(0)
	s_barrier

.LBB0_2451:
	s_or_b64 exec, exec, s[6:7]
.LBB0_2452:
	s_or_b64 exec, exec, s[2:3]
	s_waitcnt lgkmcnt(0)
	s_barrier

.LBB0_2560:
	s_or_b64 exec, exec, s[4:5]
.LBB0_2561:
	s_or_b64 exec, exec, s[0:1]
	s_waitcnt lgkmcnt(0)
	s_barrier
